# P1b schedule: chain CUs take 5 tiles, CUs 32-63 take a tenth
# speedup vs baseline: 1.0247x; 1.0247x over previous
;     __device__ __forceinline__ bool next(int i, Unit& u) const {
;     ...
;         else if (c >= 32) { if (i < 8) L = i * 224 + (c - 32); else if (i == 8 && c < 96) L = 1984 + (c - 32); else return false; }
;         else { if (i < 6) L = 1792 + i * 32 + c; else return false; }
.LBB0_412:
	v_readlane_b32 s14, v254, 9
	v_readlane_b32 s15, v254, 10
	s_add_i32 s40, s2, 1
	s_and_b64 vcc, exec, s[14:15]
	s_cbranch_vccz .LBB0_415
	s_mov_b64 s[26:27], 0
	s_cmp_lt_u32 s2, 4
	s_mov_b64 s[14:15], 0
	s_cbranch_scc0 .LBB0_416
	s_lshl_b32 s3, s40, 5
	v_readlane_b32 s14, v254, 22
	s_add_i32 s3, s14, s3
	s_mov_b64 s[14:15], -1
	s_branch .LBB0_416

;     __device__ __forceinline__ bool next(int i, Unit& u) const {
;     ...
;         else if (c >= 32) { if (i < 8) L = i * 224 + (c - 32); else if (i == 8 && c < 96) L = 1984 + (c - 32); else return false; }
;         else { if (i < 6) L = 1792 + i * 32 + c; else return false; }
.LBB0_416:
	s_and_b64 vcc, exec, s[26:27]
	s_cbranch_vccz .LBB0_421
	s_cmp_gt_u32 s2, 6
	s_mov_b64 s[26:27], -1
	s_cbranch_scc0 .LBB0_419
	s_cmp_eq_u32 s40, 8
	v_readlane_b32 s14, v254, 23
	s_cselect_b64 s[2:3], -1, 0
	v_readlane_b32 s15, v254, 24
	s_and_b64 s[14:15], s[14:15], s[2:3]
	s_mov_b64 s[26:27], 0
	v_readlane_b32 s3, v254, 25
	s_cmp_eq_u32 s40, 9
	s_cbranch_scc0 .LBB0_421
	s_cmp_lt_u32 s69, 64
	s_cbranch_scc0 .LBB0_421
	s_cmp_ge_u32 s69, 32
	s_cbranch_scc0 .LBB0_421
	s_add_i32 s3, s3, -32
	s_mov_b64 s[14:15], -1
	s_branch .LBB0_421
